# MoBA S waves read the next block's query count at the end of the previous block iteration (LDS round trip off the path to step 0)
# baseline (speedup 1.0000x reference)
;     ...
;         for (int j = -1; j < blk; ++j) {
;           {
;             const bf16_t* kp = Mk + (krow0 + (j + 1) * 256 + 64 * sw + prow) * 64 + fq * 8;
.LBB0_654:
	s_add_i32 s16, s19, 1
	s_lshl_b32 s22, s16, 15

;     ...
;             const bf16_t* kp = Mk + (krow0 + (j + 1) * 256 + 64 * sw + prow) * 64 + fq * 8;
	s_ashr_i32 s23, s22, 31
	v_lshl_add_u64 v[2:3], v[112:113], 0, s[22:23]

;     ...
;           const int n = j < 0 ? 0 : (own ? 256 : cnt[j]), ntile = (n + 15) >> 4;
;     ...
;             const bf16_t* kp = Mk + (krow0 + (j + 1) * 256 + 64 * sw + prow) * 64 + fq * 8;
; #pragma unroll
;             for (int g = 0; g < 2; ++g)
; #pragma unroll
;               for (int par = 0; par < 2; ++par) { kn[g * 2 + par][0] = *(const bf16x8*)(kp + (32 * g + 4 * par) * 64); kn[g * 2 + par][1] = *(const bf16x8*)(kp + (32 * g + 4 * par) * 64 + 32); }
;           }
;           ssteps(j, std::false_type{});
	global_load_dwordx4 v[30:33], v[2:3], off
	global_load_dwordx4 v[26:29], v[2:3], off offset:1024
	global_load_dwordx4 v[22:25], v[2:3], off offset:2048
	global_load_dwordx4 v[18:21], v[2:3], off offset:3072
	v_add_co_u32_e32 v2, vcc, 0x1000, v2
	s_cmp_lt_i32 s19, 0
	s_nop 0
	v_addc_co_u32_e32 v3, vcc, 0, v3, vcc
	global_load_dwordx4 v[14:17], v[2:3], off
	global_load_dwordx4 v[10:13], v[2:3], off offset:1024
	global_load_dwordx4 v[6:9], v[2:3], off offset:2048
	s_nop 0
	global_load_dwordx4 v[2:5], v[2:3], off offset:3072
	s_mov_b32 s17, 0
	s_cbranch_scc1 .LBB0_656
	s_waitcnt lgkmcnt(0)
	v_readfirstlane_b32 s17, v108

;     ...
;           const int n = j < 0 ? 0 : (own ? 256 : cnt[j]), ntile = (n + 15) >> 4;
;     ...
;           ssteps(j, std::false_type{});
; #pragma unroll
;           for (int a = 0; a < 4; ++a) { kf[a][0] = kn[a][0]; kf[a][1] = kn[a][1]; }
;         }
.LBB0_662:
	s_addk_i32 s14, 0x100
	s_cmp_eq_u32 s16, s18
	s_cbranch_scc1 .LBB0_665
	s_mov_b32 s19, s16
	s_lshl_b32 s98, s16, 2
	s_add_i32 s98, s98, 0x10400
	v_mov_b32_e32 v108, s98
	ds_read_b32 v108, v108
	s_waitcnt vmcnt(7)
	v_pk_mov_b32 v[34:35], v[30:31], v[30:31] op_sel:[0,1]
	v_pk_mov_b32 v[36:37], v[32:33], v[32:33] op_sel:[0,1]
	s_waitcnt vmcnt(6)
	v_pk_mov_b32 v[38:39], v[26:27], v[26:27] op_sel:[0,1]
	v_pk_mov_b32 v[40:41], v[28:29], v[28:29] op_sel:[0,1]
	s_waitcnt vmcnt(5)
	v_pk_mov_b32 v[42:43], v[22:23], v[22:23] op_sel:[0,1]
	v_pk_mov_b32 v[44:45], v[24:25], v[24:25] op_sel:[0,1]
	s_waitcnt vmcnt(4)
	v_pk_mov_b32 v[46:47], v[18:19], v[18:19] op_sel:[0,1]
	v_pk_mov_b32 v[48:49], v[20:21], v[20:21] op_sel:[0,1]
	s_waitcnt vmcnt(3)
	v_pk_mov_b32 v[50:51], v[14:15], v[14:15] op_sel:[0,1]
	v_pk_mov_b32 v[52:53], v[16:17], v[16:17] op_sel:[0,1]
	s_waitcnt vmcnt(2)
	v_pk_mov_b32 v[54:55], v[10:11], v[10:11] op_sel:[0,1]
	v_pk_mov_b32 v[56:57], v[12:13], v[12:13] op_sel:[0,1]
	s_waitcnt vmcnt(1)
	v_pk_mov_b32 v[58:59], v[6:7], v[6:7] op_sel:[0,1]
	v_pk_mov_b32 v[60:61], v[8:9], v[8:9] op_sel:[0,1]
	s_waitcnt vmcnt(0)
	v_pk_mov_b32 v[62:63], v[2:3], v[2:3] op_sel:[0,1]
	v_pk_mov_b32 v[64:65], v[4:5], v[4:5] op_sel:[0,1]
	s_branch .LBB0_654
